# cooperative-groups grid sync after the prologue replaced by the XCD-hierarchical barrier (on top of v2)
# baseline (speedup 1.0000x reference)
; #define LAS __attribute__((address_space(3)))
; __device__ __forceinline__ unsigned xb_ld(unsigned* p)              { return __hip_atomic_load(p, __ATOMIC_RELAXED, __HIP_MEMORY_SCOPE_AGENT); }
; __device__ __forceinline__ unsigned xb_add(unsigned* p, unsigned v) { return __hip_atomic_fetch_add(p, v, __ATOMIC_RELAXED, __HIP_MEMORY_SCOPE_AGENT); }
; __device__ __forceinline__ unsigned xb_xcc_id() { return (unsigned)__builtin_amdgcn_s_getreg((3 << 11) | 20) & 0xFu; }
; __device__ __forceinline__ XcdBarrier xcd_barrier_post(unsigned* bar, volatile LAS unsigned* st) {
;     XcdBarrier b; b.bar = bar; b.x = xb_xcc_id(); b.st = st;
;     if (threadIdx.x == 0) (void)xb_add(&bar[XB_XCNT(b.x)], 1u);
;     return b;
; }
; __device__ __forceinline__ void xcd_barrier_complete(unsigned* bar, unsigned x, unsigned& nloc, unsigned& nx) {
;     const unsigned G = gridDim.x * gridDim.y * gridDim.z;
;     unsigned sum, cnt, mine, sp = 0u;
;     for (;;) {
;         sum = 0u; cnt = 0u; mine = 0u;
; #pragma unroll
;         for (unsigned j = 0; j < 16; ++j) { const unsigned c = xb_ld(&bar[XB_XCNT(j)]); sum += c; cnt += (c > 0u) ? 1u : 0u; mine = (j == x) ? c : mine; }
;         if (sum == G) break;
;         __builtin_amdgcn_s_sleep(1);
;         if ((++sp & 255u) == 0u) { if (xb_ld(&bar[XB_TMO])) break; if (sp > XB_SPIN_CAP) { atomicAdd(&bar[XB_TMO], 1u); break; } }
;     }
;     nloc = mine > 0u ? mine : 1u; nx = cnt > 0u ? cnt : 1u;
; }
; __device__ __forceinline__ void xcd_barrier(const XcdBarrier& b) {
;     asm volatile("s_waitcnt vmcnt(0)" ::: "memory");
;     __syncthreads();
;     if (threadIdx.x == 0) {
;         unsigned* bar = b.bar;
;         __builtin_amdgcn_s_waitcnt(0);
;         unsigned nloc = b.st[0], nx = b.st[1];
;         if (nloc == 0u) { xcd_barrier_complete(bar, b.x, nloc, nx); b.st[0] = nloc; b.st[1] = nx; }
.LBB0_280:
	s_or_b64 exec, exec, s[8:9]
.Lxb0_311:
	s_waitcnt vmcnt(0)
	s_waitcnt lgkmcnt(0)
	s_barrier
	s_and_saveexec_b64 s[46:47], s[4:5]
	s_cbranch_execz .Lxb0_355
	s_add_i32 s6, 0, 0x20000
	s_waitcnt vmcnt(0)
	v_mov_b32_e32 v0, s6
	s_waitcnt vmcnt(0) expcnt(0) lgkmcnt(0)
	ds_read_b32 v2, v0
	s_add_i32 s6, 0, 0x20004
	v_mov_b32_e32 v0, s6
	ds_read_b32 v4, v0
	s_waitcnt lgkmcnt(1)
	v_cmp_ne_u32_e32 vcc, 0, v2
	s_cbranch_vccnz .Lxb0_326
	s_load_dword s8, s[44:45], 0x14
	s_mov_b64 s[6:7], 0x1000
	v_lshl_add_u64 v[0:1], v[156:157], 0, s[6:7]
	s_mov_b64 s[6:7], 0x1100
	v_lshl_add_u64 v[2:3], v[156:157], 0, s[6:7]
	s_waitcnt lgkmcnt(0)
	s_lshr_b32 s10, s8, 16
	s_and_b32 s8, s8, 0xffff
	s_cmp_lg_u32 s8, 0
	s_cselect_b64 s[8:9], -1, 0
	s_cmp_lg_u64 s[8:9], 0
	s_addc_u32 s8, s39, 0
	s_cmp_lg_u32 s10, 0
	s_mul_i32 s24, s8, s38
	s_cselect_b64 s[8:9], -1, 0
	s_cmp_lg_u64 s[8:9], 0
	s_mov_b64 s[6:7], 0x1200
	s_addc_u32 s8, s88, 0
	v_lshl_add_u64 v[4:5], v[156:157], 0, s[6:7]
	s_mov_b64 s[6:7], 0x1300
	s_mul_i32 s24, s24, s8
	v_lshl_add_u64 v[6:7], v[156:157], 0, s[6:7]
	s_mov_b32 s25, 1
	s_mov_b64 s[6:7], 0
	s_branch .Lxb0_316

; template <class Epi, class Sched, bool ALIGN_EPI = false, bool SP2 = false>
; __device__ __forceinline__ void gemm_phase(PG8_LAS unsigned char* lds, const Gemm g, const Sched& S, const Epi& E) {
;     const int tid = tid_fresh(), wid = __builtin_amdgcn_readfirstlane(tid >> 6), lane = tid & 63, wr = wid >> 2, wc = wid & 3, fr = lane & 15, fq = lane >> 4;
;     const int K = g.K, nt = K / BK;
;     unsigned voffA[2], voffB[2];
; #pragma unroll
;     for (int i = 0; i < 2; ++i) { int R, C; stage_rc(tid * 16 + i * 8192, R, C); const int Rb = Epi::PERM ? ((R & ~31) + perm32(R & 31)) : R;
;         voffA[i] = (unsigned)(R * K + C) * 2u; voffB[i] = (unsigned)(Rb * K + C) * 2u; }
;     const size_t kstep = (size_t)(BK * 2);
;     const size_t hstep = (size_t)HALF * K * 2;
;     const size_t tstep = 2 * hstep;
;     const unsigned ldsw = (unsigned)wid * 1024u;
;     const int aoff = lds_byte(wr * 64 + fr, fq * 8), boff = lds_byte(wc * 32 + fr, fq * 8);
;     ...
;     Unit cur, nxt; int ui = 0;
;     if (!S.next(0, cur)) return;
;     f32x4 acc[2][2][4][2];
; #pragma unroll
;     for (int a = 0; a < 2; ++a)
; #pragma unroll
;         for (int b = 0; b < 2; ++b)
; #pragma unroll
;             for (int m = 0; m < 4; ++m)
; #pragma unroll
;                 for (int n = 0; n < 2; ++n) acc[a][b][m][n] = (f32x4){0.f, 0.f, 0.f, 0.f};
;     bf16x8 At[4][2], B0[2][2], B1[2][2];
;     const char* cA = (const char*)g.A + (size_t)cur.pm * tstep; const char* cB = (const char*)g.Bt + (size_t)cur.pn * tstep;
;     S.a_ready(cur);
;     if constexpr (SP2) {
;         PG8_STAGE(PG8_SB(0, 0), cB, voffB); PG8_STAGE(PG8_SB(0, 1), cB + hstep, voffB); PG8_STAGE(PG8_SA(0, 0), cA, voffA); PG8_STAGE(PG8_SA(0, 1), cA + hstep, voffA);
;         if (wr == 1) PG8_BAR;
;         PG8_WAIT_V(2); PG8_BAR;
;         PG8_STAGE(PG8_SB(1, 0), cB + kstep, voffB); PG8_STAGE(PG8_SA(1, 0), cA + kstep, voffA); PG8_STAGE(PG8_SB(1, 1), cB + hstep + kstep, voffB);
;         PG8_WAIT_V(6); PG8_BAR;
;     } else {
;         PG8_STAGE(PG8_SB(0, 0), cB, voffB); PG8_STAGE(PG8_SA(0, 0), cA, voffA); PG8_STAGE(PG8_SB(0, 1), cB + hstep, voffB); PG8_STAGE(PG8_SA(0, 1), cA + hstep, voffA);
;         if (wr == 1) PG8_BAR;
;         PG8_WAIT_V(4); PG8_BAR;
;         PG8_STAGE(PG8_SB(1, 0), cB + kstep, voffB); PG8_STAGE(PG8_SA(1, 0), cA + kstep, voffA); PG8_STAGE(PG8_SB(1, 1), cB + hstep + kstep, voffB);
.Lxb0_355:
	s_or_b64 exec, exec, s[46:47]
	s_mov_b64 s[6:7], s[0:1]
	s_waitcnt lgkmcnt(0)
	s_barrier
	s_movk_i32 s8, 0x400
	v_mov_b64_e32 v[2:3], s[6:7]
	flat_load_dwordx2 v[0:1], v[2:3] offset:240
	flat_load_dwordx2 v[128:129], v[2:3] offset:296
	flat_load_dwordx2 v[130:131], v[2:3] offset:216
	flat_load_dwordx2 v[132:133], v[2:3] offset:200
	s_movk_i32 s6, 0x1600
	s_ashr_i32 s7, s6, 31
	s_lshr_b32 s7, s7, 24
	s_add_i32 s6, s6, s7
	s_ashr_i32 s12, s6, 8
	s_lshl_b32 s6, s12, 7
	v_mov_b32_e32 v14, v254
	s_cmp_ge_i32 s2, s6
	v_readfirstlane_b32 s7, v14
	s_cbranch_scc1 .LBB0_311
	v_lshlrev_b32_e32 v2, 4, v14
	v_add_u32_e32 v3, 0x2000, v2
	v_ashrrev_i32_e32 v4, 31, v3
	v_lshrrev_b32_e32 v4, 22, v4
	v_add_u32_e32 v4, v3, v4
	v_ashrrev_i32_e32 v4, 10, v4
	v_mul_i32_i24_e32 v5, 0x400, v4
	v_sub_u32_e32 v3, v3, v5
	v_lshrrev_b32_e32 v5, 4, v3
	v_bitop3_b32 v3, v5, v3, 32 bitop3:0x6c
	v_ashrrev_i32_e32 v5, 31, v3
	v_lshrrev_b32_e32 v5, 26, v5
	v_add_u32_e32 v5, v3, v5
	v_lshlrev_b32_e32 v7, 3, v4
	v_ashrrev_i32_e32 v6, 6, v5
	v_and_b32_e32 v7, -16, v7
	v_lshlrev_b32_e32 v4, 5, v4
	v_add_u32_e32 v7, v6, v7
	v_and_b32_e32 v15, 32, v4
	v_and_b32_e32 v4, 0xc0, v5
	v_and_b32_e32 v6, 3, v6
	s_mov_b32 s13, 0x7fffffe0
	v_lshrrev_b32_e32 v8, 2, v7
	v_lshlrev_b32_e32 v9, 1, v7
	v_sub_u32_e32 v3, v3, v4
	v_mov_b32_e32 v4, 1
	v_and_or_b32 v6, v7, s13, v6
	v_and_b32_e32 v8, 4, v8
	v_and_b32_e32 v9, 24, v9
	v_ashrrev_i16_sdwa v3, v4, sext(v3) dst_sel:DWORD dst_unused:UNUSED_PAD src0_sel:DWORD src1_sel:BYTE_0
	v_or3_b32 v6, v6, v8, v9
	v_bfe_i32 v16, v3, 0, 16
	v_mul_lo_u32 v6, v6, s8
	v_add_u32_e32 v3, v15, v16
	v_mul_lo_u32 v17, v7, s8
	v_add_lshl_u32 v134, v6, v3, 1
	v_add_lshl_u32 v136, v3, v17, 1
	v_bfe_i32 v3, v14, 27, 1
	v_lshrrev_b32_e32 v3, 22, v3
	v_add_u32_e32 v3, v2, v3
	v_and_b32_e32 v3, 0xfffffc00, v3
	v_sub_u32_e32 v2, v2, v3
	v_ashrrev_i32_e32 v5, 31, v14
	v_lshrrev_b32_e32 v3, 4, v2
	v_lshrrev_b32_e32 v5, 26, v5
	v_bitop3_b32 v3, v3, v2, 32 bitop3:0x6c
	v_ashrrev_i32_e32 v2, 31, v2
	v_add_u32_e32 v5, v14, v5
	v_lshrrev_b32_e32 v2, 26, v2
	v_ashrrev_i32_e32 v5, 6, v5
	v_add_u32_e32 v2, v3, v2
	v_lshlrev_b32_e32 v6, 3, v5
	v_ashrrev_i32_e32 v2, 6, v2
	v_and_b32_e32 v6, -16, v6
	v_add_u32_e32 v6, v2, v6
	v_and_b32_e32 v7, 3, v2
	v_and_or_b32 v7, v6, s13, v7
	s_lshr_b32 s13, s3, 29
	s_add_i32 s13, s2, s13
	s_ashr_i32 s10, s7, 6
	s_ashr_i32 s9, s8, 31
	s_lshl_b32 s31, s12, 4
	s_ashr_i32 s18, s13, 3
	s_and_b32 s13, s13, -8
	s_ashr_i32 s11, s7, 8
	s_lshl_b64 s[14:15], s[8:9], 8
	s_lshl_b64 s[16:17], s[8:9], 9
	s_lshl_b32 s29, s10, 10
	s_sub_i32 s13, s2, s13
	s_or_b32 s34, s31, 1
	s_cmp_lt_i32 s13, 0
	s_cselect_b32 s19, s34, s31
	s_lshl_b32 s35, s12, 3
	v_mul_i32_i24_e32 v2, 64, v2
	s_abs_i32 s36, s35
	v_sub_u32_e32 v2, v3, v2
	v_cvt_f32_u32_e32 v3, s36
	s_mul_i32 s13, s19, s13
	s_sub_i32 s19, 0, s36
	s_add_i32 s13, s13, s18
	v_rcp_iflag_f32_e32 v3, v3
	s_ashr_i32 s18, s13, 31
	s_bfe_i32 s37, s12, 0x1001c
	s_xor_b32 s12, s18, s37
	v_mul_f32_e32 v3, 0x4f7ffffe, v3
	v_cvt_u32_f32_e32 v3, v3
	s_abs_i32 s18, s13
	v_lshrrev_b32_e32 v8, 2, v6
	v_lshlrev_b32_e32 v9, 1, v6
	v_readfirstlane_b32 s41, v3
	s_mul_i32 s19, s19, s41
	s_mul_hi_u32 s19, s41, s19
	s_add_i32 s41, s41, s19
	s_mul_hi_u32 s19, s18, s41
	s_mul_i32 s20, s19, s36
	s_sub_i32 s18, s18, s20
	s_add_i32 s20, s19, 1
	s_sub_i32 s21, s18, s36
	s_cmp_ge_u32 s18, s36
	s_cselect_b32 s19, s20, s19
	s_cselect_b32 s18, s21, s18
	s_add_i32 s20, s19, 1
	s_cmp_ge_u32 s18, s36
	s_cselect_b32 s18, s20, s19
	s_xor_b32 s18, s18, s12
	s_sub_i32 s12, s18, s12
	s_lshl_b32 s18, s12, 3
	s_sub_i32 s19, 0x80, s18
	s_min_i32 s19, s19, 8
	s_abs_i32 s20, s19
	v_cvt_f32_u32_e32 v3, s20
	v_and_b32_e32 v8, 4, v8
	v_and_b32_e32 v9, 24, v9
	v_lshlrev_b32_e32 v5, 5, v5
	v_ashrrev_i16_sdwa v2, v4, sext(v2) dst_sel:DWORD dst_unused:UNUSED_PAD src0_sel:DWORD src1_sel:BYTE_0
	v_or3_b32 v7, v7, v8, v9
	v_and_b32_e32 v18, 32, v5
	v_bfe_i32 v19, v2, 0, 16
	v_mul_lo_u32 v7, v7, s8
	v_add_u32_e32 v2, v18, v19
	v_mul_lo_u32 v20, v6, s8
	v_add_lshl_u32 v138, v7, v2, 1
	v_add_lshl_u32 v140, v2, v20, 1
	v_rcp_iflag_f32_e32 v2, v3
	s_sub_i32 s22, 0, s20
	s_mul_i32 s12, s12, s35
	s_sub_i32 s12, s13, s12
	v_mul_f32_e32 v2, 0x4f7ffffe, v2
	v_cvt_u32_f32_e32 v2, v2
	s_abs_i32 s21, s12
	s_xor_b32 s13, s12, s19
	s_ashr_i32 s13, s13, 31
	v_readfirstlane_b32 s23, v2
	s_mul_i32 s22, s22, s23
	s_mul_hi_u32 s22, s23, s22
	s_add_i32 s23, s23, s22
	s_mul_hi_u32 s22, s21, s23
	s_mul_i32 s23, s22, s20
	s_sub_i32 s21, s21, s23
	s_add_i32 s23, s22, 1
	s_sub_i32 s24, s21, s20
	s_cmp_ge_u32 s21, s20
	s_cselect_b32 s22, s23, s22
	s_cselect_b32 s21, s24, s21
	s_add_i32 s23, s22, 1
	s_cmp_ge_u32 s21, s20
	s_cselect_b32 s20, s23, s22
	s_xor_b32 s20, s20, s13
	s_sub_i32 s66, s20, s13
	s_mul_i32 s13, s66, s19
	s_sub_i32 s12, s12, s13
	s_add_i32 s12, s12, s18
	s_ashr_i32 s18, s66, 31
	s_mul_i32 s20, s16, s18
	s_lshr_b64 s[18:19], s[8:9], 23
	s_mul_i32 s19, s18, s66
	v_mov_b32_e32 v2, s66
	s_add_i32 s19, s20, s19
	s_waitcnt vmcnt(0) lgkmcnt(0)
	v_mad_u64_u32 v[158:159], s[20:21], s16, v2, v[128:129]
	v_mov_b32_e32 v143, 0
	v_add_u32_e32 v159, s19, v159
	s_add_i32 s46, s29, 0
	v_mov_b32_e32 v139, v143
	s_ashr_i32 s13, s12, 31
	s_add_i32 m0, s46, 0x10000
	v_lshl_add_u64 v[6:7], v[158:159], 0, v[138:139]
	v_mov_b32_e32 v135, v143
	global_load_lds_dwordx4 v[6:7], off
	v_lshl_add_u64 v[8:9], v[158:159], 0, v[134:135]
	s_add_i32 m0, s46, 0x12000
	v_lshl_add_u64 v[4:5], v[158:159], 0, s[14:15]
	s_mul_i32 s13, s16, s13
	s_mul_i32 s18, s18, s12
	v_mov_b32_e32 v10, s12
	global_load_lds_dwordx4 v[8:9], off
	s_add_i32 m0, s46, 0x14000
	v_lshl_add_u64 v[2:3], v[4:5], 0, v[138:139]
	s_add_i32 s13, s13, s18
	v_mad_u64_u32 v[160:161], s[18:19], s16, v10, v[132:133]
	global_load_lds_dwordx4 v[2:3], off
	v_lshl_add_u64 v[4:5], v[4:5], 0, v[134:135]
	s_add_i32 m0, s46, 0x16000
	v_add_u32_e32 v161, s13, v161
	v_mov_b32_e32 v141, v143
	global_load_lds_dwordx4 v[4:5], off
	v_lshl_add_u64 v[10:11], v[160:161], 0, v[140:141]
	s_mov_b32 m0, s46
	v_mov_b32_e32 v137, v143
	s_add_i32 s47, s46, 0x2000
	global_load_lds_dwordx4 v[10:11], off
	v_lshl_add_u64 v[12:13], v[160:161], 0, v[136:137]
	s_mov_b32 m0, s47
	v_lshl_add_u64 v[22:23], v[160:161], 0, s[14:15]
	s_add_i32 s48, s46, 0x4000
	global_load_lds_dwordx4 v[12:13], off
	v_lshl_add_u64 v[24:25], v[22:23], 0, v[140:141]
	s_mov_b32 m0, s48
	s_add_i32 s49, s46, 0x6000
	global_load_lds_dwordx4 v[24:25], off
	v_lshl_add_u64 v[22:23], v[22:23], 0, v[136:137]
	s_mov_b32 m0, s49
	s_cmp_eq_u32 s11, 1
	global_load_lds_dwordx4 v[22:23], off
	s_cselect_b64 s[18:19], -1, 0
	s_cmp_lg_u32 s11, 1
	s_mov_b32 s21, 0
	s_cbranch_scc1 .LBB0_293
	s_barrier
